# FoX and stick-breaking epilogues: v_permlane32_swap pairs so each lane stores 16 B (4 dwordx4 instead of 8 dwordx2 per lane)
# speedup vs baseline: 1.0199x; 1.0078x over previous
.LBB0_209:
	s_or_b64 exec, exec, s[48:49]
	v_lshlrev_b32_e32 v0, 10, v129
	v_and_b32_e32 v0, 0x3000, v0
	v_add_u32_e32 v34, v120, v0
	v_ashrrev_i32_e32 v35, 31, v34
	v_lshlrev_b64 v[34:35], 11, v[34:35]
	v_lshlrev_b32_e32 v0, 7, v129
	v_lshl_add_u64 v[34:35], s[70:71], 0, v[34:35]
	v_and_b32_e32 v0, 0x180, v0
	v_lshl_add_u64 v[34:35], v[34:35], 0, v[0:1]
	v_lshlrev_b32_e32 v0, 3, v115
	v_lshl_add_u64 v[36:37], v[34:35], 0, v[0:1]
	s_mov_b64 s[38:39], 0x95c8600
	v_lshl_add_u64 v[34:35], v[36:37], 0, s[38:39]
	v_add_co_u32_e32 v36, vcc, 0x95c8000, v36
	s_nop 1
	v_addc_co_u32_e32 v37, vcc, 0, v37, vcc
	global_load_dwordx2 v[44:45], v[34:35], off
	global_load_dwordx2 v[46:47], v[34:35], off offset:16
	global_load_dwordx2 v[48:49], v[34:35], off offset:32
	global_load_dwordx2 v[50:51], v[34:35], off offset:48
	global_load_dwordx2 v[52:53], v[34:35], off offset:64
	global_load_dwordx2 v[54:55], v[34:35], off offset:80
	global_load_dwordx2 v[56:57], v[34:35], off offset:96
	global_load_dwordx2 v[58:59], v[34:35], off offset:112
	s_mov_b32 s38, 0xbfb8aa3b
	s_mov_b32 s39, 0xbfb8aa3b
	s_mov_b32 s48, 1.0
	s_mov_b32 s49, 1.0
	v_and_b32_e32 v96, 32, v216
	v_lshrrev_b32_e32 v96, 2, v96
	v_mov_b32_e32 v97, 0
	v_lshl_add_u64 v[98:99], v[34:35], 0, v[96:97]
	s_waitcnt vmcnt(0)
	v_lshlrev_b32_e32 v64, 16, v44
	v_and_b32_e32 v65, 0xffff0000, v44
	v_lshlrev_b32_e32 v66, 16, v45
	v_and_b32_e32 v67, 0xffff0000, v45
	v_lshlrev_b32_e32 v68, 16, v46
	v_and_b32_e32 v69, 0xffff0000, v46
	v_lshlrev_b32_e32 v70, 16, v47
	v_and_b32_e32 v71, 0xffff0000, v47
	v_lshlrev_b32_e32 v72, 16, v48
	v_and_b32_e32 v73, 0xffff0000, v48
	v_lshlrev_b32_e32 v74, 16, v49
	v_and_b32_e32 v75, 0xffff0000, v49
	v_lshlrev_b32_e32 v76, 16, v50
	v_and_b32_e32 v77, 0xffff0000, v50
	v_lshlrev_b32_e32 v78, 16, v51
	v_and_b32_e32 v79, 0xffff0000, v51
	v_pk_mul_f32 v[80:81], v[64:65], s[38:39]
	v_pk_mul_f32 v[82:83], v[66:67], s[38:39]
	v_pk_mul_f32 v[84:85], v[68:69], s[38:39]
	v_pk_mul_f32 v[86:87], v[70:71], s[38:39]
	v_pk_mul_f32 v[88:89], v[72:73], s[38:39]
	v_pk_mul_f32 v[90:91], v[74:75], s[38:39]
	v_pk_mul_f32 v[92:93], v[76:77], s[38:39]
	v_pk_mul_f32 v[94:95], v[78:79], s[38:39]
	v_exp_f32_e32 v80, v80
	v_exp_f32_e32 v81, v81
	v_exp_f32_e32 v82, v82
	v_exp_f32_e32 v83, v83
	v_exp_f32_e32 v84, v84
	v_exp_f32_e32 v85, v85
	v_exp_f32_e32 v86, v86
	v_exp_f32_e32 v87, v87
	v_exp_f32_e32 v88, v88
	v_exp_f32_e32 v89, v89
	v_exp_f32_e32 v90, v90
	v_exp_f32_e32 v91, v91
	v_exp_f32_e32 v92, v92
	v_exp_f32_e32 v93, v93
	v_exp_f32_e32 v94, v94
	v_exp_f32_e32 v95, v95
	v_pk_add_f32 v[80:81], v[80:81], s[48:49]
	v_pk_add_f32 v[82:83], v[82:83], s[48:49]
	v_pk_add_f32 v[84:85], v[84:85], s[48:49]
	v_pk_add_f32 v[86:87], v[86:87], s[48:49]
	v_pk_add_f32 v[88:89], v[88:89], s[48:49]
	v_pk_add_f32 v[90:91], v[90:91], s[48:49]
	v_pk_add_f32 v[92:93], v[92:93], s[48:49]
	v_pk_add_f32 v[94:95], v[94:95], s[48:49]
	v_rcp_f32_e32 v80, v80
	v_rcp_f32_e32 v81, v81
	v_rcp_f32_e32 v82, v82
	v_rcp_f32_e32 v83, v83
	v_rcp_f32_e32 v84, v84
	v_rcp_f32_e32 v85, v85
	v_rcp_f32_e32 v86, v86
	v_rcp_f32_e32 v87, v87
	v_rcp_f32_e32 v88, v88
	v_rcp_f32_e32 v89, v89
	v_rcp_f32_e32 v90, v90
	v_rcp_f32_e32 v91, v91
	v_rcp_f32_e32 v92, v92
	v_rcp_f32_e32 v93, v93
	v_rcp_f32_e32 v94, v94
	v_rcp_f32_e32 v95, v95
	v_pk_mul_f32 v[80:81], v[80:81], v[64:65]
	v_pk_mul_f32 v[82:83], v[82:83], v[66:67]
	v_pk_mul_f32 v[84:85], v[84:85], v[68:69]
	v_pk_mul_f32 v[86:87], v[86:87], v[70:71]
	v_pk_mul_f32 v[88:89], v[88:89], v[72:73]
	v_pk_mul_f32 v[90:91], v[90:91], v[74:75]
	v_pk_mul_f32 v[92:93], v[92:93], v[76:77]
	v_pk_mul_f32 v[94:95], v[94:95], v[78:79]
	v_pk_mul_f32 v[80:81], v[2:3], v[80:81]
	v_pk_mul_f32 v[82:83], v[4:5], v[82:83]
	v_pk_mul_f32 v[84:85], v[6:7], v[84:85]
	v_pk_mul_f32 v[86:87], v[8:9], v[86:87]
	v_pk_mul_f32 v[88:89], v[10:11], v[88:89]
	v_pk_mul_f32 v[90:91], v[12:13], v[90:91]
	v_pk_mul_f32 v[92:93], v[14:15], v[92:93]
	v_pk_mul_f32 v[94:95], v[16:17], v[94:95]
	v_cvt_pk_bf16_f32 v64, v80, v81
	v_cvt_pk_bf16_f32 v65, v82, v83
	v_cvt_pk_bf16_f32 v66, v84, v85
	v_cvt_pk_bf16_f32 v67, v86, v87
	v_cvt_pk_bf16_f32 v68, v88, v89
	v_cvt_pk_bf16_f32 v69, v90, v91
	v_cvt_pk_bf16_f32 v70, v92, v93
	v_cvt_pk_bf16_f32 v71, v94, v95
	s_nop 1
	v_permlane32_swap_b32 v64, v66
	v_permlane32_swap_b32 v65, v67
	v_permlane32_swap_b32 v68, v70
	v_permlane32_swap_b32 v69, v71
	global_store_dwordx4 v[98:99], v[64:67], off
	global_store_dwordx4 v[98:99], v[68:71], off offset:32
	s_nop 1
	v_lshlrev_b32_e32 v64, 16, v52
	v_and_b32_e32 v65, 0xffff0000, v52
	v_lshlrev_b32_e32 v66, 16, v53
	v_and_b32_e32 v67, 0xffff0000, v53
	v_lshlrev_b32_e32 v68, 16, v54
	v_and_b32_e32 v69, 0xffff0000, v54
	v_lshlrev_b32_e32 v70, 16, v55
	v_and_b32_e32 v71, 0xffff0000, v55
	v_lshlrev_b32_e32 v72, 16, v56
	v_and_b32_e32 v73, 0xffff0000, v56
	v_lshlrev_b32_e32 v74, 16, v57
	v_and_b32_e32 v75, 0xffff0000, v57
	v_lshlrev_b32_e32 v76, 16, v58
	v_and_b32_e32 v77, 0xffff0000, v58
	v_lshlrev_b32_e32 v78, 16, v59
	v_and_b32_e32 v79, 0xffff0000, v59
	v_pk_mul_f32 v[80:81], v[64:65], s[38:39]
	v_pk_mul_f32 v[82:83], v[66:67], s[38:39]
	v_pk_mul_f32 v[84:85], v[68:69], s[38:39]
	v_pk_mul_f32 v[86:87], v[70:71], s[38:39]
	v_pk_mul_f32 v[88:89], v[72:73], s[38:39]
	v_pk_mul_f32 v[90:91], v[74:75], s[38:39]
	v_pk_mul_f32 v[92:93], v[76:77], s[38:39]
	v_pk_mul_f32 v[94:95], v[78:79], s[38:39]
	v_exp_f32_e32 v80, v80
	v_exp_f32_e32 v81, v81
	v_exp_f32_e32 v82, v82
	v_exp_f32_e32 v83, v83
	v_exp_f32_e32 v84, v84
	v_exp_f32_e32 v85, v85
	v_exp_f32_e32 v86, v86
	v_exp_f32_e32 v87, v87
	v_exp_f32_e32 v88, v88
	v_exp_f32_e32 v89, v89
	v_exp_f32_e32 v90, v90
	v_exp_f32_e32 v91, v91
	v_exp_f32_e32 v92, v92
	v_exp_f32_e32 v93, v93
	v_exp_f32_e32 v94, v94
	v_exp_f32_e32 v95, v95
	v_pk_add_f32 v[80:81], v[80:81], s[48:49]
	v_pk_add_f32 v[82:83], v[82:83], s[48:49]
	v_pk_add_f32 v[84:85], v[84:85], s[48:49]
	v_pk_add_f32 v[86:87], v[86:87], s[48:49]
	v_pk_add_f32 v[88:89], v[88:89], s[48:49]
	v_pk_add_f32 v[90:91], v[90:91], s[48:49]
	v_pk_add_f32 v[92:93], v[92:93], s[48:49]
	v_pk_add_f32 v[94:95], v[94:95], s[48:49]
	v_rcp_f32_e32 v80, v80
	v_rcp_f32_e32 v81, v81
	v_rcp_f32_e32 v82, v82
	v_rcp_f32_e32 v83, v83
	v_rcp_f32_e32 v84, v84
	v_rcp_f32_e32 v85, v85
	v_rcp_f32_e32 v86, v86
	v_rcp_f32_e32 v87, v87
	v_rcp_f32_e32 v88, v88
	v_rcp_f32_e32 v89, v89
	v_rcp_f32_e32 v90, v90
	v_rcp_f32_e32 v91, v91
	v_rcp_f32_e32 v92, v92
	v_rcp_f32_e32 v93, v93
	v_rcp_f32_e32 v94, v94
	v_rcp_f32_e32 v95, v95
	v_pk_mul_f32 v[80:81], v[80:81], v[64:65]
	v_pk_mul_f32 v[82:83], v[82:83], v[66:67]
	v_pk_mul_f32 v[84:85], v[84:85], v[68:69]
	v_pk_mul_f32 v[86:87], v[86:87], v[70:71]
	v_pk_mul_f32 v[88:89], v[88:89], v[72:73]
	v_pk_mul_f32 v[90:91], v[90:91], v[74:75]
	v_pk_mul_f32 v[92:93], v[92:93], v[76:77]
	v_pk_mul_f32 v[94:95], v[94:95], v[78:79]
	v_pk_mul_f32 v[80:81], v[18:19], v[80:81]
	v_pk_mul_f32 v[82:83], v[20:21], v[82:83]
	v_pk_mul_f32 v[84:85], v[22:23], v[84:85]
	v_pk_mul_f32 v[86:87], v[24:25], v[86:87]
	v_pk_mul_f32 v[88:89], v[26:27], v[88:89]
	v_pk_mul_f32 v[90:91], v[28:29], v[90:91]
	v_pk_mul_f32 v[92:93], v[30:31], v[92:93]
	v_pk_mul_f32 v[94:95], v[32:33], v[94:95]
	v_cvt_pk_bf16_f32 v64, v80, v81
	v_cvt_pk_bf16_f32 v65, v82, v83
	v_cvt_pk_bf16_f32 v66, v84, v85
	v_cvt_pk_bf16_f32 v67, v86, v87
	v_cvt_pk_bf16_f32 v68, v88, v89
	v_cvt_pk_bf16_f32 v69, v90, v91
	v_cvt_pk_bf16_f32 v70, v92, v93
	v_cvt_pk_bf16_f32 v71, v94, v95
	s_nop 1
	v_permlane32_swap_b32 v64, v66
	v_permlane32_swap_b32 v65, v67
	v_permlane32_swap_b32 v68, v70
	v_permlane32_swap_b32 v69, v71
	global_store_dwordx4 v[98:99], v[64:67], off offset:64
	global_store_dwordx4 v[98:99], v[68:71], off offset:96
	s_waitcnt lgkmcnt(0)
	s_barrier

.LBB0_257:
	s_or_b64 exec, exec, s[42:43]
	v_xor_b32_e32 v0, 32, v216
	v_add_u32_e32 v2, 64, v113
	v_cmp_lt_i32_e32 vcc, v0, v2
	v_readlane_b32 s38, v251, 27
	v_readlane_b32 s39, v251, 28
	v_cndmask_b32_e32 v0, v216, v0, vcc
	v_lshlrev_b32_e32 v0, 2, v0
	ds_bpermute_b32 v0, v0, v148
	s_waitcnt lgkmcnt(0)
	v_add_f32_e32 v0, v148, v0
	v_rcp_f32_e32 v4, v0
	v_lshlrev_b32_e32 v0, 9, v120
	v_and_b32_e32 v0, 0x3000, v0
	v_add_u32_e32 v2, v112, v0
	v_ashrrev_i32_e32 v3, 31, v2
	v_lshlrev_b64 v[2:3], 11, v[2:3]
	v_lshlrev_b32_e32 v0, 7, v120
	v_lshl_add_u64 v[2:3], s[38:39], 0, v[2:3]
	v_and_b32_e32 v0, 0x380, v0
	v_lshl_add_u64 v[2:3], v[2:3], 0, v[0:1]
	v_lshlrev_b32_e32 v0, 3, v121
	v_lshl_add_u64 v[2:3], v[2:3], 0, v[0:1]
	global_load_dwordx2 v[192:193], v[2:3], off
	global_load_dwordx2 v[194:195], v[2:3], off offset:16
	global_load_dwordx2 v[196:197], v[2:3], off offset:32
	global_load_dwordx2 v[198:199], v[2:3], off offset:48
	global_load_dwordx2 v[200:201], v[2:3], off offset:64
	global_load_dwordx2 v[202:203], v[2:3], off offset:80
	global_load_dwordx2 v[204:205], v[2:3], off offset:96
	global_load_dwordx2 v[206:207], v[2:3], off offset:112
	s_mov_b32 s44, 0xbfb8aa3b
	s_mov_b32 s45, 0xbfb8aa3b
	s_mov_b32 s46, 1.0
	s_mov_b32 s47, 1.0
	v_and_b32_e32 v96, 32, v216
	v_lshrrev_b32_e32 v96, 2, v96
	v_mov_b32_e32 v97, 0
	v_lshl_add_u64 v[98:99], v[2:3], 0, v[96:97]
	v_pk_mul_f32 v[32:33], v[32:33], v[4:5] op_sel_hi:[1,0]
	v_pk_mul_f32 v[34:35], v[34:35], v[4:5] op_sel_hi:[1,0]
	v_pk_mul_f32 v[36:37], v[36:37], v[4:5] op_sel_hi:[1,0]
	v_pk_mul_f32 v[38:39], v[38:39], v[4:5] op_sel_hi:[1,0]
	v_pk_mul_f32 v[40:41], v[40:41], v[4:5] op_sel_hi:[1,0]
	v_pk_mul_f32 v[42:43], v[42:43], v[4:5] op_sel_hi:[1,0]
	v_pk_mul_f32 v[44:45], v[44:45], v[4:5] op_sel_hi:[1,0]
	v_pk_mul_f32 v[46:47], v[46:47], v[4:5] op_sel_hi:[1,0]
	v_pk_mul_f32 v[16:17], v[16:17], v[4:5] op_sel_hi:[1,0]
	v_pk_mul_f32 v[18:19], v[18:19], v[4:5] op_sel_hi:[1,0]
	v_pk_mul_f32 v[20:21], v[20:21], v[4:5] op_sel_hi:[1,0]
	v_pk_mul_f32 v[22:23], v[22:23], v[4:5] op_sel_hi:[1,0]
	v_pk_mul_f32 v[24:25], v[24:25], v[4:5] op_sel_hi:[1,0]
	v_pk_mul_f32 v[26:27], v[26:27], v[4:5] op_sel_hi:[1,0]
	v_pk_mul_f32 v[28:29], v[28:29], v[4:5] op_sel_hi:[1,0]
	v_pk_mul_f32 v[30:31], v[30:31], v[4:5] op_sel_hi:[1,0]
	s_waitcnt vmcnt(0)
	v_lshlrev_b32_e32 v64, 16, v192
	v_and_b32_e32 v65, 0xffff0000, v192
	v_lshlrev_b32_e32 v66, 16, v193
	v_and_b32_e32 v67, 0xffff0000, v193
	v_lshlrev_b32_e32 v68, 16, v194
	v_and_b32_e32 v69, 0xffff0000, v194
	v_lshlrev_b32_e32 v70, 16, v195
	v_and_b32_e32 v71, 0xffff0000, v195
	v_lshlrev_b32_e32 v72, 16, v196
	v_and_b32_e32 v73, 0xffff0000, v196
	v_lshlrev_b32_e32 v74, 16, v197
	v_and_b32_e32 v75, 0xffff0000, v197
	v_lshlrev_b32_e32 v76, 16, v198
	v_and_b32_e32 v77, 0xffff0000, v198
	v_lshlrev_b32_e32 v78, 16, v199
	v_and_b32_e32 v79, 0xffff0000, v199
	v_pk_mul_f32 v[80:81], v[64:65], s[44:45]
	v_pk_mul_f32 v[82:83], v[66:67], s[44:45]
	v_pk_mul_f32 v[84:85], v[68:69], s[44:45]
	v_pk_mul_f32 v[86:87], v[70:71], s[44:45]
	v_pk_mul_f32 v[88:89], v[72:73], s[44:45]
	v_pk_mul_f32 v[90:91], v[74:75], s[44:45]
	v_pk_mul_f32 v[92:93], v[76:77], s[44:45]
	v_pk_mul_f32 v[94:95], v[78:79], s[44:45]
	v_exp_f32_e32 v80, v80
	v_exp_f32_e32 v81, v81
	v_exp_f32_e32 v82, v82
	v_exp_f32_e32 v83, v83
	v_exp_f32_e32 v84, v84
	v_exp_f32_e32 v85, v85
	v_exp_f32_e32 v86, v86
	v_exp_f32_e32 v87, v87
	v_exp_f32_e32 v88, v88
	v_exp_f32_e32 v89, v89
	v_exp_f32_e32 v90, v90
	v_exp_f32_e32 v91, v91
	v_exp_f32_e32 v92, v92
	v_exp_f32_e32 v93, v93
	v_exp_f32_e32 v94, v94
	v_exp_f32_e32 v95, v95
	v_pk_add_f32 v[80:81], v[80:81], s[46:47]
	v_pk_add_f32 v[82:83], v[82:83], s[46:47]
	v_pk_add_f32 v[84:85], v[84:85], s[46:47]
	v_pk_add_f32 v[86:87], v[86:87], s[46:47]
	v_pk_add_f32 v[88:89], v[88:89], s[46:47]
	v_pk_add_f32 v[90:91], v[90:91], s[46:47]
	v_pk_add_f32 v[92:93], v[92:93], s[46:47]
	v_pk_add_f32 v[94:95], v[94:95], s[46:47]
	v_rcp_f32_e32 v80, v80
	v_rcp_f32_e32 v81, v81
	v_rcp_f32_e32 v82, v82
	v_rcp_f32_e32 v83, v83
	v_rcp_f32_e32 v84, v84
	v_rcp_f32_e32 v85, v85
	v_rcp_f32_e32 v86, v86
	v_rcp_f32_e32 v87, v87
	v_rcp_f32_e32 v88, v88
	v_rcp_f32_e32 v89, v89
	v_rcp_f32_e32 v90, v90
	v_rcp_f32_e32 v91, v91
	v_rcp_f32_e32 v92, v92
	v_rcp_f32_e32 v93, v93
	v_rcp_f32_e32 v94, v94
	v_rcp_f32_e32 v95, v95
	v_pk_mul_f32 v[80:81], v[80:81], v[64:65]
	v_pk_mul_f32 v[82:83], v[82:83], v[66:67]
	v_pk_mul_f32 v[84:85], v[84:85], v[68:69]
	v_pk_mul_f32 v[86:87], v[86:87], v[70:71]
	v_pk_mul_f32 v[88:89], v[88:89], v[72:73]
	v_pk_mul_f32 v[90:91], v[90:91], v[74:75]
	v_pk_mul_f32 v[92:93], v[92:93], v[76:77]
	v_pk_mul_f32 v[94:95], v[94:95], v[78:79]
	v_pk_mul_f32 v[80:81], v[32:33], v[80:81]
	v_pk_mul_f32 v[82:83], v[34:35], v[82:83]
	v_pk_mul_f32 v[84:85], v[36:37], v[84:85]
	v_pk_mul_f32 v[86:87], v[38:39], v[86:87]
	v_pk_mul_f32 v[88:89], v[40:41], v[88:89]
	v_pk_mul_f32 v[90:91], v[42:43], v[90:91]
	v_pk_mul_f32 v[92:93], v[44:45], v[92:93]
	v_pk_mul_f32 v[94:95], v[46:47], v[94:95]
	v_cvt_pk_bf16_f32 v64, v80, v81
	v_cvt_pk_bf16_f32 v65, v82, v83
	v_cvt_pk_bf16_f32 v66, v84, v85
	v_cvt_pk_bf16_f32 v67, v86, v87
	v_cvt_pk_bf16_f32 v68, v88, v89
	v_cvt_pk_bf16_f32 v69, v90, v91
	v_cvt_pk_bf16_f32 v70, v92, v93
	v_cvt_pk_bf16_f32 v71, v94, v95
	s_nop 1
	v_permlane32_swap_b32 v64, v66
	v_permlane32_swap_b32 v65, v67
	v_permlane32_swap_b32 v68, v70
	v_permlane32_swap_b32 v69, v71
	global_store_dwordx4 v[98:99], v[64:67], off
	global_store_dwordx4 v[98:99], v[68:71], off offset:32
	s_nop 1
	v_lshlrev_b32_e32 v64, 16, v200
	v_and_b32_e32 v65, 0xffff0000, v200
	v_lshlrev_b32_e32 v66, 16, v201
	v_and_b32_e32 v67, 0xffff0000, v201
	v_lshlrev_b32_e32 v68, 16, v202
	v_and_b32_e32 v69, 0xffff0000, v202
	v_lshlrev_b32_e32 v70, 16, v203
	v_and_b32_e32 v71, 0xffff0000, v203
	v_lshlrev_b32_e32 v72, 16, v204
	v_and_b32_e32 v73, 0xffff0000, v204
	v_lshlrev_b32_e32 v74, 16, v205
	v_and_b32_e32 v75, 0xffff0000, v205
	v_lshlrev_b32_e32 v76, 16, v206
	v_and_b32_e32 v77, 0xffff0000, v206
	v_lshlrev_b32_e32 v78, 16, v207
	v_and_b32_e32 v79, 0xffff0000, v207
	v_pk_mul_f32 v[80:81], v[64:65], s[44:45]
	v_pk_mul_f32 v[82:83], v[66:67], s[44:45]
	v_pk_mul_f32 v[84:85], v[68:69], s[44:45]
	v_pk_mul_f32 v[86:87], v[70:71], s[44:45]
	v_pk_mul_f32 v[88:89], v[72:73], s[44:45]
	v_pk_mul_f32 v[90:91], v[74:75], s[44:45]
	v_pk_mul_f32 v[92:93], v[76:77], s[44:45]
	v_pk_mul_f32 v[94:95], v[78:79], s[44:45]
	v_exp_f32_e32 v80, v80
	v_exp_f32_e32 v81, v81
	v_exp_f32_e32 v82, v82
	v_exp_f32_e32 v83, v83
	v_exp_f32_e32 v84, v84
	v_exp_f32_e32 v85, v85
	v_exp_f32_e32 v86, v86
	v_exp_f32_e32 v87, v87
	v_exp_f32_e32 v88, v88
	v_exp_f32_e32 v89, v89
	v_exp_f32_e32 v90, v90
	v_exp_f32_e32 v91, v91
	v_exp_f32_e32 v92, v92
	v_exp_f32_e32 v93, v93
	v_exp_f32_e32 v94, v94
	v_exp_f32_e32 v95, v95
	v_pk_add_f32 v[80:81], v[80:81], s[46:47]
	v_pk_add_f32 v[82:83], v[82:83], s[46:47]
	v_pk_add_f32 v[84:85], v[84:85], s[46:47]
	v_pk_add_f32 v[86:87], v[86:87], s[46:47]
	v_pk_add_f32 v[88:89], v[88:89], s[46:47]
	v_pk_add_f32 v[90:91], v[90:91], s[46:47]
	v_pk_add_f32 v[92:93], v[92:93], s[46:47]
	v_pk_add_f32 v[94:95], v[94:95], s[46:47]
	v_rcp_f32_e32 v80, v80
	v_rcp_f32_e32 v81, v81
	v_rcp_f32_e32 v82, v82
	v_rcp_f32_e32 v83, v83
	v_rcp_f32_e32 v84, v84
	v_rcp_f32_e32 v85, v85
	v_rcp_f32_e32 v86, v86
	v_rcp_f32_e32 v87, v87
	v_rcp_f32_e32 v88, v88
	v_rcp_f32_e32 v89, v89
	v_rcp_f32_e32 v90, v90
	v_rcp_f32_e32 v91, v91
	v_rcp_f32_e32 v92, v92
	v_rcp_f32_e32 v93, v93
	v_rcp_f32_e32 v94, v94
	v_rcp_f32_e32 v95, v95
	v_pk_mul_f32 v[80:81], v[80:81], v[64:65]
	v_pk_mul_f32 v[82:83], v[82:83], v[66:67]
	v_pk_mul_f32 v[84:85], v[84:85], v[68:69]
	v_pk_mul_f32 v[86:87], v[86:87], v[70:71]
	v_pk_mul_f32 v[88:89], v[88:89], v[72:73]
	v_pk_mul_f32 v[90:91], v[90:91], v[74:75]
	v_pk_mul_f32 v[92:93], v[92:93], v[76:77]
	v_pk_mul_f32 v[94:95], v[94:95], v[78:79]
	v_pk_mul_f32 v[80:81], v[16:17], v[80:81]
	v_pk_mul_f32 v[82:83], v[18:19], v[82:83]
	v_pk_mul_f32 v[84:85], v[20:21], v[84:85]
	v_pk_mul_f32 v[86:87], v[22:23], v[86:87]
	v_pk_mul_f32 v[88:89], v[24:25], v[88:89]
	v_pk_mul_f32 v[90:91], v[26:27], v[90:91]
	v_pk_mul_f32 v[92:93], v[28:29], v[92:93]
	v_pk_mul_f32 v[94:95], v[30:31], v[94:95]
	v_cvt_pk_bf16_f32 v64, v80, v81
	v_cvt_pk_bf16_f32 v65, v82, v83
	v_cvt_pk_bf16_f32 v66, v84, v85
	v_cvt_pk_bf16_f32 v67, v86, v87
	v_cvt_pk_bf16_f32 v68, v88, v89
	v_cvt_pk_bf16_f32 v69, v90, v91
	v_cvt_pk_bf16_f32 v70, v92, v93
	v_cvt_pk_bf16_f32 v71, v94, v95
	s_nop 1
	v_permlane32_swap_b32 v64, v66
	v_permlane32_swap_b32 v65, v67
	v_permlane32_swap_b32 v68, v70
	v_permlane32_swap_b32 v69, v71
	global_store_dwordx4 v[98:99], v[64:67], off offset:64
	global_store_dwordx4 v[98:99], v[68:71], off offset:96
